# topk expert-id look-ups: compare/select chains software-pipelined over three mask registers (no s_nop wait states between v_cmp and v_cndmask)
# speedup vs baseline: 1.0010x; 1.0010x over previous
.LBB0_1064:
	s_andn2_saveexec_b64 s[54:55], s[54:55]
	s_cbranch_execz .LBB0_1055
	v_not_b32_e32 v33, v34
	v_bitop3_b32 v35, v34, s78, v34 bitop3:0xc
	v_bfe_u32 v33, v33, 4, 4
	v_cmp_gt_u32_e32 vcc, 16, v35
	v_cmp_eq_u32_e64 s[98:99], 1, v33
	v_cmp_eq_u32_e64 s[100:101], 2, v33
	v_cndmask_b32_e32 v35, 0, v85, vcc
	v_bitop3_b32 v34, v34, 15, v34 bitop3:0xc
	v_not_b32_e32 v36, v2
	v_cmp_eq_u32_e32 vcc, 3, v33
	v_cndmask_b32_e64 v35, v35, v86, s[98:99]
	v_bitop3_b32 v37, v2, s78, v2 bitop3:0xc
	v_bitop3_b32 v2, v2, 15, v2 bitop3:0xc
	v_cmp_eq_u32_e64 s[98:99], 4, v33
	v_cndmask_b32_e64 v35, v35, v87, s[100:101]
	v_bfe_u32 v36, v36, 4, 4
	s_lshl_b64 s[56:57], s[48:49], 2
	v_cmp_eq_u32_e64 s[100:101], 5, v33
	v_cndmask_b32_e32 v35, v35, v88, vcc
	s_add_u32 s52, s52, s56
	s_addc_u32 s53, s53, s57
	v_cmp_eq_u32_e32 vcc, 6, v33
	v_cndmask_b32_e64 v35, v35, v89, s[98:99]
	v_lshl_add_u64 v[16:17], v[16:17], 2, s[52:53]
	v_cmp_eq_u32_e64 s[98:99], 7, v33
	v_cndmask_b32_e64 v35, v35, v90, s[100:101]
	v_cmp_eq_u32_e64 s[100:101], 8, v33
	v_cndmask_b32_e32 v35, v35, v91, vcc
	v_cmp_eq_u32_e32 vcc, 9, v33
	v_cndmask_b32_e64 v35, v35, v92, s[98:99]
	v_cmp_eq_u32_e64 s[98:99], 10, v33
	v_cndmask_b32_e64 v35, v35, v93, s[100:101]
	v_cmp_eq_u32_e64 s[100:101], 11, v33
	v_cndmask_b32_e32 v35, v35, v94, vcc
	v_cmp_eq_u32_e32 vcc, 12, v33
	v_cndmask_b32_e64 v35, v35, v95, s[98:99]
	v_cmp_eq_u32_e64 s[98:99], 13, v33
	v_cndmask_b32_e64 v35, v35, v96, s[100:101]
	v_cmp_eq_u32_e64 s[100:101], 14, v33
	v_cndmask_b32_e32 v35, v35, v97, vcc
	v_cmp_eq_u32_e32 vcc, 15, v33
	v_cndmask_b32_e64 v35, v35, v98, s[98:99]
	v_cndmask_b32_e64 v35, v35, v99, s[100:101]
	v_cndmask_b32_e32 v33, v35, v100, vcc
	v_cmp_eq_u32_e32 vcc, 0, v34
	s_nop 1
	v_cndmask_b32_e32 v35, 0, v12, vcc
	v_cmp_eq_u32_e32 vcc, 1, v34
	s_nop 1
	v_cndmask_b32_e32 v35, v35, v18, vcc
	v_cmp_eq_u32_e32 vcc, 2, v34
	s_nop 1
	v_cndmask_b32_e32 v35, v35, v19, vcc
	v_cmp_eq_u32_e32 vcc, 3, v34
	s_nop 1
	v_cndmask_b32_e32 v35, v35, v20, vcc
	v_cmp_eq_u32_e32 vcc, 4, v34
	s_nop 1
	v_cndmask_b32_e32 v35, v35, v21, vcc
	v_cmp_eq_u32_e32 vcc, 5, v34
	s_nop 1
	v_cndmask_b32_e32 v35, v35, v22, vcc
	v_cmp_eq_u32_e32 vcc, 6, v34
	s_nop 1
	v_cndmask_b32_e32 v35, v35, v23, vcc
	v_cmp_eq_u32_e32 vcc, 7, v34
	s_nop 1
	v_cndmask_b32_e32 v35, v35, v24, vcc
	v_cmp_eq_u32_e32 vcc, 8, v34
	s_nop 1
	v_cndmask_b32_e32 v35, v35, v25, vcc
	v_cmp_eq_u32_e32 vcc, 9, v34
	s_nop 1
	v_cndmask_b32_e32 v35, v35, v26, vcc
	v_cmp_eq_u32_e32 vcc, 10, v34
	s_nop 1
	v_cndmask_b32_e32 v35, v35, v27, vcc
	v_cmp_eq_u32_e32 vcc, 11, v34
	s_nop 1
	v_cndmask_b32_e32 v35, v35, v28, vcc
	v_cmp_eq_u32_e32 vcc, 12, v34
	s_nop 1
	v_cndmask_b32_e32 v35, v35, v29, vcc
	v_cmp_eq_u32_e32 vcc, 13, v34
	s_nop 1
	v_cndmask_b32_e32 v35, v35, v30, vcc
	v_cmp_eq_u32_e32 vcc, 14, v34
	s_nop 1
	v_cndmask_b32_e32 v35, v35, v31, vcc
	v_cmp_eq_u32_e32 vcc, 0, v2
	v_cmp_eq_u32_e64 s[98:99], 1, v2
	v_cmp_eq_u32_e64 s[100:101], 2, v2
	v_cndmask_b32_e32 v38, 0, v12, vcc
	v_cmp_eq_u32_e32 vcc, 3, v2
	v_cndmask_b32_e64 v38, v38, v18, s[98:99]
	v_cmp_eq_u32_e64 s[98:99], 4, v2
	v_cndmask_b32_e64 v38, v38, v19, s[100:101]
	v_cmp_eq_u32_e64 s[100:101], 5, v2
	v_cndmask_b32_e32 v38, v38, v20, vcc
	v_cmp_eq_u32_e32 vcc, 6, v2
	v_cndmask_b32_e64 v38, v38, v21, s[98:99]
	v_cmp_eq_u32_e64 s[98:99], 7, v2
	v_cndmask_b32_e64 v38, v38, v22, s[100:101]
	v_cmp_eq_u32_e64 s[100:101], 8, v2
	v_cndmask_b32_e32 v38, v38, v23, vcc
	v_cmp_eq_u32_e32 vcc, 9, v2
	v_cndmask_b32_e64 v38, v38, v24, s[98:99]
	v_cmp_eq_u32_e64 s[98:99], 10, v2
	v_cndmask_b32_e64 v38, v38, v25, s[100:101]
	v_cmp_eq_u32_e64 s[100:101], 11, v2
	v_cndmask_b32_e32 v38, v38, v26, vcc
	v_cmp_eq_u32_e32 vcc, 12, v2
	v_cndmask_b32_e64 v38, v38, v27, s[98:99]
	v_cmp_eq_u32_e64 s[98:99], 13, v2
	v_cndmask_b32_e64 v38, v38, v28, s[100:101]
	v_cmp_eq_u32_e64 s[100:101], 14, v2
	v_cndmask_b32_e32 v38, v38, v29, vcc
	v_cmp_eq_u32_e32 vcc, 15, v2
	v_cndmask_b32_e64 v38, v38, v30, s[98:99]
	v_cndmask_b32_e64 v38, v38, v31, s[100:101]
	v_cndmask_b32_e32 v2, v38, v3, vcc
	v_cmp_gt_u32_e32 vcc, 16, v37
	v_cmp_eq_u32_e64 s[98:99], 1, v36
	v_cmp_eq_u32_e64 s[100:101], 2, v36
	v_cndmask_b32_e32 v37, 0, v85, vcc
	v_and_b32_e32 v2, 0x7f, v2
	v_cmp_eq_u32_e32 vcc, 3, v36
	v_cndmask_b32_e64 v37, v37, v86, s[98:99]
	v_cmp_eq_u32_e64 s[98:99], 4, v36
	v_cndmask_b32_e64 v37, v37, v87, s[100:101]
	v_cmp_eq_u32_e64 s[100:101], 5, v36
	v_cndmask_b32_e32 v37, v37, v88, vcc
	v_cmp_eq_u32_e32 vcc, 6, v36
	v_cndmask_b32_e64 v37, v37, v89, s[98:99]
	v_cmp_eq_u32_e64 s[98:99], 7, v36
	v_cndmask_b32_e64 v37, v37, v90, s[100:101]
	v_cmp_eq_u32_e64 s[100:101], 8, v36
	v_cndmask_b32_e32 v37, v37, v91, vcc
	v_cmp_eq_u32_e32 vcc, 9, v36
	v_cndmask_b32_e64 v37, v37, v92, s[98:99]
	v_cmp_eq_u32_e64 s[98:99], 10, v36
	v_cndmask_b32_e64 v37, v37, v93, s[100:101]
	v_cmp_eq_u32_e64 s[100:101], 11, v36
	v_cndmask_b32_e32 v37, v37, v94, vcc
	v_cmp_eq_u32_e32 vcc, 12, v36
	v_cndmask_b32_e64 v37, v37, v95, s[98:99]
	v_cmp_eq_u32_e64 s[98:99], 13, v36
	v_cndmask_b32_e64 v37, v37, v96, s[100:101]
	v_cmp_eq_u32_e64 s[100:101], 14, v36
	v_cndmask_b32_e32 v37, v37, v97, vcc
	v_cmp_eq_u32_e32 vcc, 15, v36
	v_cndmask_b32_e64 v37, v37, v98, s[98:99]
	v_cndmask_b32_e64 v37, v37, v99, s[100:101]
	v_cndmask_b32_e32 v36, v37, v100, vcc
	v_lshlrev_b32_e32 v36, 7, v36
	v_and_b32_e32 v36, 0x3f80, v36
	v_bitop3_b32 v2, v2, s82, v36 bitop3:0x36
	v_not_b32_e32 v36, v1
	v_bitop3_b32 v37, v1, s78, v1 bitop3:0xc
	v_bitop3_b32 v1, v1, 15, v1 bitop3:0xc
	v_cmp_eq_u32_e32 vcc, 0, v1
	v_cmp_eq_u32_e64 s[98:99], 1, v1
	v_cmp_eq_u32_e64 s[100:101], 2, v1
	v_cndmask_b32_e32 v38, 0, v12, vcc
	v_bfe_u32 v36, v36, 4, 4
	v_cmp_eq_u32_e32 vcc, 3, v1
	v_cndmask_b32_e64 v38, v38, v18, s[98:99]
	v_cmp_eq_u32_e64 s[98:99], 4, v1
	v_cndmask_b32_e64 v38, v38, v19, s[100:101]
	v_cmp_eq_u32_e64 s[100:101], 5, v1
	v_cndmask_b32_e32 v38, v38, v20, vcc
	v_cmp_eq_u32_e32 vcc, 6, v1
	v_cndmask_b32_e64 v38, v38, v21, s[98:99]
	v_cmp_eq_u32_e64 s[98:99], 7, v1
	v_cndmask_b32_e64 v38, v38, v22, s[100:101]
	v_cmp_eq_u32_e64 s[100:101], 8, v1
	v_cndmask_b32_e32 v38, v38, v23, vcc
	v_cmp_eq_u32_e32 vcc, 9, v1
	v_cndmask_b32_e64 v38, v38, v24, s[98:99]
	v_cmp_eq_u32_e64 s[98:99], 10, v1
	v_cndmask_b32_e64 v38, v38, v25, s[100:101]
	v_cmp_eq_u32_e64 s[100:101], 11, v1
	v_cndmask_b32_e32 v38, v38, v26, vcc
	v_cmp_eq_u32_e32 vcc, 12, v1
	v_cndmask_b32_e64 v38, v38, v27, s[98:99]
	v_cmp_eq_u32_e64 s[98:99], 13, v1
	v_cndmask_b32_e64 v38, v38, v28, s[100:101]
	v_cmp_eq_u32_e64 s[100:101], 14, v1
	v_cndmask_b32_e32 v38, v38, v29, vcc
	v_cmp_eq_u32_e32 vcc, 15, v1
	v_cndmask_b32_e64 v38, v38, v30, s[98:99]
	v_cndmask_b32_e64 v38, v38, v31, s[100:101]
	v_cndmask_b32_e32 v1, v38, v3, vcc
	v_cmp_gt_u32_e32 vcc, 16, v37
	v_cmp_eq_u32_e64 s[98:99], 1, v36
	v_cmp_eq_u32_e64 s[100:101], 2, v36
	v_cndmask_b32_e32 v37, 0, v85, vcc
	v_and_b32_e32 v1, 0x7f, v1
	v_cmp_eq_u32_e32 vcc, 3, v36
	v_cndmask_b32_e64 v37, v37, v86, s[98:99]
	v_cmp_eq_u32_e64 s[98:99], 4, v36
	v_cndmask_b32_e64 v37, v37, v87, s[100:101]
	v_cmp_eq_u32_e64 s[100:101], 5, v36
	v_cndmask_b32_e32 v37, v37, v88, vcc
	v_cmp_eq_u32_e32 vcc, 6, v36
	v_cndmask_b32_e64 v37, v37, v89, s[98:99]
	v_cmp_eq_u32_e64 s[98:99], 7, v36
	v_cndmask_b32_e64 v37, v37, v90, s[100:101]
	v_cmp_eq_u32_e64 s[100:101], 8, v36
	v_cndmask_b32_e32 v37, v37, v91, vcc
	v_cmp_eq_u32_e32 vcc, 9, v36
	v_cndmask_b32_e64 v37, v37, v92, s[98:99]
	v_cmp_eq_u32_e64 s[98:99], 10, v36
	v_cndmask_b32_e64 v37, v37, v93, s[100:101]
	v_cmp_eq_u32_e64 s[100:101], 11, v36
	v_cndmask_b32_e32 v37, v37, v94, vcc
	v_cmp_eq_u32_e32 vcc, 12, v36
	v_cndmask_b32_e64 v37, v37, v95, s[98:99]
	v_cmp_eq_u32_e64 s[98:99], 13, v36
	v_cndmask_b32_e64 v37, v37, v96, s[100:101]
	v_cmp_eq_u32_e64 s[100:101], 14, v36
	v_cndmask_b32_e32 v37, v37, v97, vcc
	v_cmp_eq_u32_e32 vcc, 15, v36
	v_cndmask_b32_e64 v37, v37, v98, s[98:99]
	v_cndmask_b32_e64 v37, v37, v99, s[100:101]
	v_cndmask_b32_e32 v36, v37, v100, vcc
	v_lshlrev_b32_e32 v36, 7, v36
	v_and_b32_e32 v36, 0x3f80, v36
	v_bitop3_b32 v1, v1, s82, v36 bitop3:0x36
	v_not_b32_e32 v36, v0
	v_bitop3_b32 v37, v0, s78, v0 bitop3:0xc
	v_bitop3_b32 v0, v0, 15, v0 bitop3:0xc
	v_cmp_eq_u32_e32 vcc, 0, v0
	v_cmp_eq_u32_e64 s[98:99], 1, v0
	v_cmp_eq_u32_e64 s[100:101], 2, v0
	v_cndmask_b32_e32 v38, 0, v12, vcc
	v_bfe_u32 v36, v36, 4, 4
	v_cmp_eq_u32_e32 vcc, 3, v0
	v_cndmask_b32_e64 v38, v38, v18, s[98:99]
	v_cmp_eq_u32_e64 s[98:99], 4, v0
	v_cndmask_b32_e64 v38, v38, v19, s[100:101]
	v_cmp_eq_u32_e64 s[100:101], 5, v0
	v_cndmask_b32_e32 v38, v38, v20, vcc
	v_cmp_eq_u32_e32 vcc, 6, v0
	v_cndmask_b32_e64 v38, v38, v21, s[98:99]
	v_cmp_eq_u32_e64 s[98:99], 7, v0
	v_cndmask_b32_e64 v38, v38, v22, s[100:101]
	v_cmp_eq_u32_e64 s[100:101], 8, v0
	v_cndmask_b32_e32 v38, v38, v23, vcc
	v_cmp_eq_u32_e32 vcc, 9, v0
	v_cndmask_b32_e64 v38, v38, v24, s[98:99]
	v_cmp_eq_u32_e64 s[98:99], 10, v0
	v_cndmask_b32_e64 v38, v38, v25, s[100:101]
	v_cmp_eq_u32_e64 s[100:101], 11, v0
	v_cndmask_b32_e32 v38, v38, v26, vcc
	v_cmp_eq_u32_e32 vcc, 12, v0
	v_cndmask_b32_e64 v38, v38, v27, s[98:99]
	v_cmp_eq_u32_e64 s[98:99], 13, v0
	v_cndmask_b32_e64 v38, v38, v28, s[100:101]
	v_cmp_eq_u32_e64 s[100:101], 14, v0
	v_cndmask_b32_e32 v38, v38, v29, vcc
	v_cmp_eq_u32_e32 vcc, 15, v0
	v_cndmask_b32_e64 v38, v38, v30, s[98:99]
	v_cndmask_b32_e64 v38, v38, v31, s[100:101]
	v_cndmask_b32_e32 v0, v38, v3, vcc
	v_cmp_gt_u32_e32 vcc, 16, v37
	v_cmp_eq_u32_e64 s[98:99], 1, v36
	v_cmp_eq_u32_e64 s[100:101], 2, v36
	v_cndmask_b32_e32 v37, 0, v85, vcc
	v_and_b32_e32 v0, 0x7f, v0
	v_cmp_eq_u32_e32 vcc, 3, v36
	v_cndmask_b32_e64 v37, v37, v86, s[98:99]
	v_cmp_eq_u32_e64 s[98:99], 4, v36
	v_cndmask_b32_e64 v37, v37, v87, s[100:101]
	v_cmp_eq_u32_e64 s[100:101], 5, v36
	v_cndmask_b32_e32 v37, v37, v88, vcc
	v_cmp_eq_u32_e32 vcc, 6, v36
	v_cndmask_b32_e64 v37, v37, v89, s[98:99]
	v_cmp_eq_u32_e64 s[98:99], 7, v36
	v_cndmask_b32_e64 v37, v37, v90, s[100:101]
	v_cmp_eq_u32_e64 s[100:101], 8, v36
	v_cndmask_b32_e32 v37, v37, v91, vcc
	v_cmp_eq_u32_e32 vcc, 9, v36
	v_cndmask_b32_e64 v37, v37, v92, s[98:99]
	v_cmp_eq_u32_e64 s[98:99], 10, v36
	v_cndmask_b32_e64 v37, v37, v93, s[100:101]
	v_cmp_eq_u32_e64 s[100:101], 11, v36
	v_cndmask_b32_e32 v37, v37, v94, vcc
	v_cmp_eq_u32_e32 vcc, 12, v36
	v_cndmask_b32_e64 v37, v37, v95, s[98:99]
	v_cmp_eq_u32_e64 s[98:99], 13, v36
	v_cndmask_b32_e64 v37, v37, v96, s[100:101]
	v_cmp_eq_u32_e64 s[100:101], 14, v36
	v_cndmask_b32_e32 v37, v37, v97, vcc
	v_cmp_eq_u32_e32 vcc, 15, v36
	v_cndmask_b32_e64 v37, v37, v98, s[98:99]
	v_cndmask_b32_e64 v37, v37, v99, s[100:101]
	v_cndmask_b32_e32 v36, v37, v100, vcc
	v_lshlrev_b32_e32 v36, 7, v36
	v_and_b32_e32 v36, 0x3f80, v36
	v_bitop3_b32 v0, v0, s82, v36 bitop3:0x36
	v_not_b32_e32 v36, v7
	v_bitop3_b32 v37, v7, s78, v7 bitop3:0xc
	v_bitop3_b32 v7, v7, 15, v7 bitop3:0xc
	v_cmp_eq_u32_e32 vcc, 0, v7
	v_cmp_eq_u32_e64 s[98:99], 1, v7
	v_cmp_eq_u32_e64 s[100:101], 2, v7
	v_cndmask_b32_e32 v38, 0, v12, vcc
	v_bfe_u32 v36, v36, 4, 4
	v_cmp_eq_u32_e32 vcc, 3, v7
	v_cndmask_b32_e64 v38, v38, v18, s[98:99]
	v_cmp_eq_u32_e64 s[98:99], 4, v7
	v_cndmask_b32_e64 v38, v38, v19, s[100:101]
	v_cmp_eq_u32_e64 s[100:101], 5, v7
	v_cndmask_b32_e32 v38, v38, v20, vcc
	v_cmp_eq_u32_e32 vcc, 6, v7
	v_cndmask_b32_e64 v38, v38, v21, s[98:99]
	v_cmp_eq_u32_e64 s[98:99], 7, v7
	v_cndmask_b32_e64 v38, v38, v22, s[100:101]
	v_cmp_eq_u32_e64 s[100:101], 8, v7
	v_cndmask_b32_e32 v38, v38, v23, vcc
	v_cmp_eq_u32_e32 vcc, 9, v7
	v_cndmask_b32_e64 v38, v38, v24, s[98:99]
	v_cmp_eq_u32_e64 s[98:99], 10, v7
	v_cndmask_b32_e64 v38, v38, v25, s[100:101]
	v_cmp_eq_u32_e64 s[100:101], 11, v7
	v_cndmask_b32_e32 v38, v38, v26, vcc
	v_cmp_eq_u32_e32 vcc, 12, v7
	v_cndmask_b32_e64 v38, v38, v27, s[98:99]
	v_cmp_eq_u32_e64 s[98:99], 13, v7
	v_cndmask_b32_e64 v38, v38, v28, s[100:101]
	v_cmp_eq_u32_e64 s[100:101], 14, v7
	v_cndmask_b32_e32 v38, v38, v29, vcc
	v_cmp_eq_u32_e32 vcc, 15, v7
	v_cndmask_b32_e64 v38, v38, v30, s[98:99]
	v_cndmask_b32_e64 v38, v38, v31, s[100:101]
	v_cndmask_b32_e32 v7, v38, v3, vcc
	v_cmp_gt_u32_e32 vcc, 16, v37
	v_cmp_eq_u32_e64 s[98:99], 1, v36
	v_cmp_eq_u32_e64 s[100:101], 2, v36
	v_cndmask_b32_e32 v37, 0, v85, vcc
	v_and_b32_e32 v7, 0x7f, v7
	v_cmp_eq_u32_e32 vcc, 3, v36
	v_cndmask_b32_e64 v37, v37, v86, s[98:99]
	v_cmp_eq_u32_e64 s[98:99], 4, v36
	v_cndmask_b32_e64 v37, v37, v87, s[100:101]
	v_cmp_eq_u32_e64 s[100:101], 5, v36
	v_cndmask_b32_e32 v37, v37, v88, vcc
	v_cmp_eq_u32_e32 vcc, 6, v36
	v_cndmask_b32_e64 v37, v37, v89, s[98:99]
	v_cmp_eq_u32_e64 s[98:99], 7, v36
	v_cndmask_b32_e64 v37, v37, v90, s[100:101]
	v_cmp_eq_u32_e64 s[100:101], 8, v36
	v_cndmask_b32_e32 v37, v37, v91, vcc
	v_cmp_eq_u32_e32 vcc, 9, v36
	v_cndmask_b32_e64 v37, v37, v92, s[98:99]
	v_cmp_eq_u32_e64 s[98:99], 10, v36
	v_cndmask_b32_e64 v37, v37, v93, s[100:101]
	v_cmp_eq_u32_e64 s[100:101], 11, v36
	v_cndmask_b32_e32 v37, v37, v94, vcc
	v_cmp_eq_u32_e32 vcc, 12, v36
	v_cndmask_b32_e64 v37, v37, v95, s[98:99]
	v_cmp_eq_u32_e64 s[98:99], 13, v36
	v_cndmask_b32_e64 v37, v37, v96, s[100:101]
	v_cmp_eq_u32_e64 s[100:101], 14, v36
	v_cndmask_b32_e32 v37, v37, v97, vcc
	v_cmp_eq_u32_e32 vcc, 15, v36
	v_cndmask_b32_e64 v37, v37, v98, s[98:99]
	v_cndmask_b32_e64 v37, v37, v99, s[100:101]
	v_cndmask_b32_e32 v36, v37, v100, vcc
	v_lshlrev_b32_e32 v36, 7, v36
	v_and_b32_e32 v36, 0x3f80, v36
	v_bitop3_b32 v7, v7, s82, v36 bitop3:0x36
	v_not_b32_e32 v36, v6
	v_bitop3_b32 v37, v6, s78, v6 bitop3:0xc
	v_bitop3_b32 v6, v6, 15, v6 bitop3:0xc
	v_cmp_eq_u32_e32 vcc, 0, v6
	v_cmp_eq_u32_e64 s[98:99], 1, v6
	v_cmp_eq_u32_e64 s[100:101], 2, v6
	v_cndmask_b32_e32 v38, 0, v12, vcc
	v_bfe_u32 v36, v36, 4, 4
	v_cmp_eq_u32_e32 vcc, 3, v6
	v_cndmask_b32_e64 v38, v38, v18, s[98:99]
	v_cmp_eq_u32_e64 s[98:99], 4, v6
	v_cndmask_b32_e64 v38, v38, v19, s[100:101]
	v_cmp_eq_u32_e64 s[100:101], 5, v6
	v_cndmask_b32_e32 v38, v38, v20, vcc
	v_cmp_eq_u32_e32 vcc, 6, v6
	v_cndmask_b32_e64 v38, v38, v21, s[98:99]
	v_cmp_eq_u32_e64 s[98:99], 7, v6
	v_cndmask_b32_e64 v38, v38, v22, s[100:101]
	v_cmp_eq_u32_e64 s[100:101], 8, v6
	v_cndmask_b32_e32 v38, v38, v23, vcc
	v_cmp_eq_u32_e32 vcc, 9, v6
	v_cndmask_b32_e64 v38, v38, v24, s[98:99]
	v_cmp_eq_u32_e64 s[98:99], 10, v6
	v_cndmask_b32_e64 v38, v38, v25, s[100:101]
	v_cmp_eq_u32_e64 s[100:101], 11, v6
	v_cndmask_b32_e32 v38, v38, v26, vcc
	v_cmp_eq_u32_e32 vcc, 12, v6
	v_cndmask_b32_e64 v38, v38, v27, s[98:99]
	v_cmp_eq_u32_e64 s[98:99], 13, v6
	v_cndmask_b32_e64 v38, v38, v28, s[100:101]
	v_cmp_eq_u32_e64 s[100:101], 14, v6
	v_cndmask_b32_e32 v38, v38, v29, vcc
	v_cmp_eq_u32_e32 vcc, 15, v6
	v_cndmask_b32_e64 v38, v38, v30, s[98:99]
	v_cndmask_b32_e64 v38, v38, v31, s[100:101]
	v_cndmask_b32_e32 v6, v38, v3, vcc
	v_cmp_gt_u32_e32 vcc, 16, v37
	v_cmp_eq_u32_e64 s[98:99], 1, v36
	v_cmp_eq_u32_e64 s[100:101], 2, v36
	v_cndmask_b32_e32 v37, 0, v85, vcc
	v_and_b32_e32 v6, 0x7f, v6
	v_cmp_eq_u32_e32 vcc, 3, v36
	v_cndmask_b32_e64 v37, v37, v86, s[98:99]
	v_cmp_eq_u32_e64 s[98:99], 4, v36
	v_cndmask_b32_e64 v37, v37, v87, s[100:101]
	v_cmp_eq_u32_e64 s[100:101], 5, v36
	v_cndmask_b32_e32 v37, v37, v88, vcc
	v_cmp_eq_u32_e32 vcc, 6, v36
	v_cndmask_b32_e64 v37, v37, v89, s[98:99]
	v_cmp_eq_u32_e64 s[98:99], 7, v36
	v_cndmask_b32_e64 v37, v37, v90, s[100:101]
	v_cmp_eq_u32_e64 s[100:101], 8, v36
	v_cndmask_b32_e32 v37, v37, v91, vcc
	v_cmp_eq_u32_e32 vcc, 9, v36
	v_cndmask_b32_e64 v37, v37, v92, s[98:99]
	v_cmp_eq_u32_e64 s[98:99], 10, v36
	v_cndmask_b32_e64 v37, v37, v93, s[100:101]
	v_cmp_eq_u32_e64 s[100:101], 11, v36
	v_cndmask_b32_e32 v37, v37, v94, vcc
	v_cmp_eq_u32_e32 vcc, 12, v36
	v_cndmask_b32_e64 v37, v37, v95, s[98:99]
	v_cmp_eq_u32_e64 s[98:99], 13, v36
	v_cndmask_b32_e64 v37, v37, v96, s[100:101]
	v_cmp_eq_u32_e64 s[100:101], 14, v36
	v_cndmask_b32_e32 v37, v37, v97, vcc
	v_cmp_eq_u32_e32 vcc, 15, v36
	v_cndmask_b32_e64 v37, v37, v98, s[98:99]
	v_cndmask_b32_e64 v37, v37, v99, s[100:101]
	v_cndmask_b32_e32 v36, v37, v100, vcc
	v_lshlrev_b32_e32 v36, 7, v36
	v_and_b32_e32 v36, 0x3f80, v36
	v_bitop3_b32 v6, v6, s82, v36 bitop3:0x36
	v_not_b32_e32 v36, v5
	v_bitop3_b32 v37, v5, s78, v5 bitop3:0xc
	v_bitop3_b32 v5, v5, 15, v5 bitop3:0xc
	v_cmp_eq_u32_e32 vcc, 0, v5
	v_cmp_eq_u32_e64 s[98:99], 1, v5
	v_cmp_eq_u32_e64 s[100:101], 2, v5
	v_cndmask_b32_e32 v38, 0, v12, vcc
	v_bfe_u32 v36, v36, 4, 4
	v_cmp_eq_u32_e32 vcc, 3, v5
	v_cndmask_b32_e64 v38, v38, v18, s[98:99]
	v_cmp_eq_u32_e64 s[98:99], 4, v5
	v_cndmask_b32_e64 v38, v38, v19, s[100:101]
	v_cmp_eq_u32_e64 s[100:101], 5, v5
	v_cndmask_b32_e32 v38, v38, v20, vcc
	v_cmp_eq_u32_e32 vcc, 6, v5
	v_cndmask_b32_e64 v38, v38, v21, s[98:99]
	v_cmp_eq_u32_e64 s[98:99], 7, v5
	v_cndmask_b32_e64 v38, v38, v22, s[100:101]
	v_cmp_eq_u32_e64 s[100:101], 8, v5
	v_cndmask_b32_e32 v38, v38, v23, vcc
	v_cmp_eq_u32_e32 vcc, 9, v5
	v_cndmask_b32_e64 v38, v38, v24, s[98:99]
	v_cmp_eq_u32_e64 s[98:99], 10, v5
	v_cndmask_b32_e64 v38, v38, v25, s[100:101]
	v_cmp_eq_u32_e64 s[100:101], 11, v5
	v_cndmask_b32_e32 v38, v38, v26, vcc
	v_cmp_eq_u32_e32 vcc, 12, v5
	v_cndmask_b32_e64 v38, v38, v27, s[98:99]
	v_cmp_eq_u32_e64 s[98:99], 13, v5
	v_cndmask_b32_e64 v38, v38, v28, s[100:101]
	v_cmp_eq_u32_e64 s[100:101], 14, v5
	v_cndmask_b32_e32 v38, v38, v29, vcc
	v_cmp_eq_u32_e32 vcc, 15, v5
	v_cndmask_b32_e64 v38, v38, v30, s[98:99]
	v_cndmask_b32_e64 v38, v38, v31, s[100:101]
	v_cndmask_b32_e32 v5, v38, v3, vcc
	v_cmp_gt_u32_e32 vcc, 16, v37
	v_cmp_eq_u32_e64 s[98:99], 1, v36
	v_cmp_eq_u32_e64 s[100:101], 2, v36
	v_cndmask_b32_e32 v37, 0, v85, vcc
	v_and_b32_e32 v5, 0x7f, v5
	v_cmp_eq_u32_e32 vcc, 3, v36
	v_cndmask_b32_e64 v37, v37, v86, s[98:99]
	v_cmp_eq_u32_e64 s[98:99], 4, v36
	v_cndmask_b32_e64 v37, v37, v87, s[100:101]
	v_cmp_eq_u32_e64 s[100:101], 5, v36
	v_cndmask_b32_e32 v37, v37, v88, vcc
	v_cmp_eq_u32_e32 vcc, 6, v36
	v_cndmask_b32_e64 v37, v37, v89, s[98:99]
	v_cmp_eq_u32_e64 s[98:99], 7, v36
	v_cndmask_b32_e64 v37, v37, v90, s[100:101]
	v_cmp_eq_u32_e64 s[100:101], 8, v36
	v_cndmask_b32_e32 v37, v37, v91, vcc
	v_cmp_eq_u32_e32 vcc, 9, v36
	v_cndmask_b32_e64 v37, v37, v92, s[98:99]
	v_cmp_eq_u32_e64 s[98:99], 10, v36
	v_cndmask_b32_e64 v37, v37, v93, s[100:101]
	v_cmp_eq_u32_e64 s[100:101], 11, v36
	v_cndmask_b32_e32 v37, v37, v94, vcc
	v_cmp_eq_u32_e32 vcc, 12, v36
	v_cndmask_b32_e64 v37, v37, v95, s[98:99]
	v_cmp_eq_u32_e64 s[98:99], 13, v36
	v_cndmask_b32_e64 v37, v37, v96, s[100:101]
	v_cmp_eq_u32_e64 s[100:101], 14, v36
	v_cndmask_b32_e32 v37, v37, v97, vcc
	v_cmp_eq_u32_e32 vcc, 15, v36
	v_cndmask_b32_e64 v37, v37, v98, s[98:99]
	v_cndmask_b32_e64 v37, v37, v99, s[100:101]
	v_cndmask_b32_e32 v36, v37, v100, vcc
	v_lshlrev_b32_e32 v36, 7, v36
	v_and_b32_e32 v36, 0x3f80, v36
	v_bitop3_b32 v5, v5, s82, v36 bitop3:0x36
	v_not_b32_e32 v36, v4
	v_bitop3_b32 v37, v4, s78, v4 bitop3:0xc
	v_bitop3_b32 v4, v4, 15, v4 bitop3:0xc
	v_cmp_eq_u32_e32 vcc, 0, v4
	v_cmp_eq_u32_e64 s[98:99], 1, v4
	v_cmp_eq_u32_e64 s[100:101], 2, v4
	v_cndmask_b32_e32 v38, 0, v12, vcc
	v_bfe_u32 v36, v36, 4, 4
	v_cmp_eq_u32_e32 vcc, 3, v4
	v_cndmask_b32_e64 v38, v38, v18, s[98:99]
	v_cmp_eq_u32_e64 s[98:99], 4, v4
	v_cndmask_b32_e64 v38, v38, v19, s[100:101]
	v_cmp_eq_u32_e64 s[100:101], 5, v4
	v_cndmask_b32_e32 v38, v38, v20, vcc
	v_cmp_eq_u32_e32 vcc, 6, v4
	v_cndmask_b32_e64 v38, v38, v21, s[98:99]
	v_cmp_eq_u32_e64 s[98:99], 7, v4
	v_cndmask_b32_e64 v38, v38, v22, s[100:101]
	v_cmp_eq_u32_e64 s[100:101], 8, v4
	v_cndmask_b32_e32 v38, v38, v23, vcc
	v_cmp_eq_u32_e32 vcc, 9, v4
	v_cndmask_b32_e64 v38, v38, v24, s[98:99]
	v_cmp_eq_u32_e64 s[98:99], 10, v4
	v_cndmask_b32_e64 v38, v38, v25, s[100:101]
	v_cmp_eq_u32_e64 s[100:101], 11, v4
	v_cndmask_b32_e32 v38, v38, v26, vcc
	v_cmp_eq_u32_e32 vcc, 12, v4
	v_cndmask_b32_e64 v38, v38, v27, s[98:99]
	v_cmp_eq_u32_e64 s[98:99], 13, v4
	v_cndmask_b32_e64 v38, v38, v28, s[100:101]
	v_cmp_eq_u32_e64 s[100:101], 14, v4
	v_cndmask_b32_e32 v38, v38, v29, vcc
	v_cmp_eq_u32_e32 vcc, 15, v4
	v_cndmask_b32_e64 v38, v38, v30, s[98:99]
	v_cndmask_b32_e64 v38, v38, v31, s[100:101]
	v_cndmask_b32_e32 v4, v38, v3, vcc
	v_cmp_gt_u32_e32 vcc, 16, v37
	v_cmp_eq_u32_e64 s[98:99], 1, v36
	v_cmp_eq_u32_e64 s[100:101], 2, v36
	v_cndmask_b32_e32 v37, 0, v85, vcc
	v_and_b32_e32 v4, 0x7f, v4
	v_cmp_eq_u32_e32 vcc, 3, v36
	v_cndmask_b32_e64 v37, v37, v86, s[98:99]
	v_cmp_eq_u32_e64 s[98:99], 4, v36
	v_cndmask_b32_e64 v37, v37, v87, s[100:101]
	v_cmp_eq_u32_e64 s[100:101], 5, v36
	v_cndmask_b32_e32 v37, v37, v88, vcc
	v_cmp_eq_u32_e32 vcc, 6, v36
	v_cndmask_b32_e64 v37, v37, v89, s[98:99]
	v_cmp_eq_u32_e64 s[98:99], 7, v36
	v_cndmask_b32_e64 v37, v37, v90, s[100:101]
	v_cmp_eq_u32_e64 s[100:101], 8, v36
	v_cndmask_b32_e32 v37, v37, v91, vcc
	v_cmp_eq_u32_e32 vcc, 9, v36
	v_cndmask_b32_e64 v37, v37, v92, s[98:99]
	v_cmp_eq_u32_e64 s[98:99], 10, v36
	v_cndmask_b32_e64 v37, v37, v93, s[100:101]
	v_cmp_eq_u32_e64 s[100:101], 11, v36
	v_cndmask_b32_e32 v37, v37, v94, vcc
	v_cmp_eq_u32_e32 vcc, 12, v36
	v_cndmask_b32_e64 v37, v37, v95, s[98:99]
	v_cmp_eq_u32_e64 s[98:99], 13, v36
	v_cndmask_b32_e64 v37, v37, v96, s[100:101]
	v_cmp_eq_u32_e64 s[100:101], 14, v36
	v_cndmask_b32_e32 v37, v37, v97, vcc
	v_cmp_eq_u32_e32 vcc, 15, v36
	v_cndmask_b32_e64 v37, v37, v98, s[98:99]
	v_cndmask_b32_e64 v37, v37, v99, s[100:101]
	v_cndmask_b32_e32 v36, v37, v100, vcc
	v_lshlrev_b32_e32 v36, 7, v36
	v_and_b32_e32 v36, 0x3f80, v36
	v_bitop3_b32 v4, v4, s82, v36 bitop3:0x36
	v_not_b32_e32 v36, v11
	v_bitop3_b32 v37, v11, s78, v11 bitop3:0xc
	v_bitop3_b32 v11, v11, 15, v11 bitop3:0xc
	v_cmp_eq_u32_e32 vcc, 0, v11
	v_cmp_eq_u32_e64 s[98:99], 1, v11
	v_cmp_eq_u32_e64 s[100:101], 2, v11
	v_cndmask_b32_e32 v38, 0, v12, vcc
	v_bfe_u32 v36, v36, 4, 4
	v_cmp_eq_u32_e32 vcc, 3, v11
	v_cndmask_b32_e64 v38, v38, v18, s[98:99]
	v_cmp_eq_u32_e64 s[98:99], 4, v11
	v_cndmask_b32_e64 v38, v38, v19, s[100:101]
	v_cmp_eq_u32_e64 s[100:101], 5, v11
	v_cndmask_b32_e32 v38, v38, v20, vcc
	v_cmp_eq_u32_e32 vcc, 6, v11
	v_cndmask_b32_e64 v38, v38, v21, s[98:99]
	v_cmp_eq_u32_e64 s[98:99], 7, v11
	v_cndmask_b32_e64 v38, v38, v22, s[100:101]
	v_cmp_eq_u32_e64 s[100:101], 8, v11
	v_cndmask_b32_e32 v38, v38, v23, vcc
	v_cmp_eq_u32_e32 vcc, 9, v11
	v_cndmask_b32_e64 v38, v38, v24, s[98:99]
	v_cmp_eq_u32_e64 s[98:99], 10, v11
	v_cndmask_b32_e64 v38, v38, v25, s[100:101]
	v_cmp_eq_u32_e64 s[100:101], 11, v11
	v_cndmask_b32_e32 v38, v38, v26, vcc
	v_cmp_eq_u32_e32 vcc, 12, v11
	v_cndmask_b32_e64 v38, v38, v27, s[98:99]
	v_cmp_eq_u32_e64 s[98:99], 13, v11
	v_cndmask_b32_e64 v38, v38, v28, s[100:101]
	v_cmp_eq_u32_e64 s[100:101], 14, v11
	v_cndmask_b32_e32 v38, v38, v29, vcc
	v_cmp_eq_u32_e32 vcc, 15, v11
	v_cndmask_b32_e64 v38, v38, v30, s[98:99]
	v_cndmask_b32_e64 v38, v38, v31, s[100:101]
	v_cndmask_b32_e32 v11, v38, v3, vcc
	v_cmp_gt_u32_e32 vcc, 16, v37
	v_cmp_eq_u32_e64 s[98:99], 1, v36
	v_cmp_eq_u32_e64 s[100:101], 2, v36
	v_cndmask_b32_e32 v37, 0, v85, vcc
	v_and_b32_e32 v11, 0x7f, v11
	v_cmp_eq_u32_e32 vcc, 3, v36
	v_cndmask_b32_e64 v37, v37, v86, s[98:99]
	v_cmp_eq_u32_e64 s[98:99], 4, v36
	v_cndmask_b32_e64 v37, v37, v87, s[100:101]
	v_cmp_eq_u32_e64 s[100:101], 5, v36
	v_cndmask_b32_e32 v37, v37, v88, vcc
	v_cmp_eq_u32_e32 vcc, 6, v36
	v_cndmask_b32_e64 v37, v37, v89, s[98:99]
	v_cmp_eq_u32_e64 s[98:99], 7, v36
	v_cndmask_b32_e64 v37, v37, v90, s[100:101]
	v_cmp_eq_u32_e64 s[100:101], 8, v36
	v_cndmask_b32_e32 v37, v37, v91, vcc
	v_cmp_eq_u32_e32 vcc, 9, v36
	v_cndmask_b32_e64 v37, v37, v92, s[98:99]
	v_cmp_eq_u32_e64 s[98:99], 10, v36
	v_cndmask_b32_e64 v37, v37, v93, s[100:101]
	v_cmp_eq_u32_e64 s[100:101], 11, v36
	v_cndmask_b32_e32 v37, v37, v94, vcc
	v_cmp_eq_u32_e32 vcc, 12, v36
	v_cndmask_b32_e64 v37, v37, v95, s[98:99]
	v_cmp_eq_u32_e64 s[98:99], 13, v36
	v_cndmask_b32_e64 v37, v37, v96, s[100:101]
	v_cmp_eq_u32_e64 s[100:101], 14, v36
	v_cndmask_b32_e32 v37, v37, v97, vcc
	v_cmp_eq_u32_e32 vcc, 15, v36
	v_cndmask_b32_e64 v37, v37, v98, s[98:99]
	v_cndmask_b32_e64 v37, v37, v99, s[100:101]
	v_cndmask_b32_e32 v36, v37, v100, vcc
	v_lshlrev_b32_e32 v36, 7, v36
	v_and_b32_e32 v36, 0x3f80, v36
	v_bitop3_b32 v11, v11, s82, v36 bitop3:0x36
	v_not_b32_e32 v36, v10
	v_bitop3_b32 v37, v10, s78, v10 bitop3:0xc
	v_bitop3_b32 v10, v10, 15, v10 bitop3:0xc
	v_cmp_eq_u32_e32 vcc, 0, v10
	v_cmp_eq_u32_e64 s[98:99], 1, v10
	v_cmp_eq_u32_e64 s[100:101], 2, v10
	v_cndmask_b32_e32 v38, 0, v12, vcc
	v_bfe_u32 v36, v36, 4, 4
	v_cmp_eq_u32_e32 vcc, 3, v10
	v_cndmask_b32_e64 v38, v38, v18, s[98:99]
	v_cmp_eq_u32_e64 s[98:99], 4, v10
	v_cndmask_b32_e64 v38, v38, v19, s[100:101]
	v_cmp_eq_u32_e64 s[100:101], 5, v10
	v_cndmask_b32_e32 v38, v38, v20, vcc
	v_cmp_eq_u32_e32 vcc, 6, v10
	v_cndmask_b32_e64 v38, v38, v21, s[98:99]
	v_cmp_eq_u32_e64 s[98:99], 7, v10
	v_cndmask_b32_e64 v38, v38, v22, s[100:101]
	v_cmp_eq_u32_e64 s[100:101], 8, v10
	v_cndmask_b32_e32 v38, v38, v23, vcc
	v_cmp_eq_u32_e32 vcc, 9, v10
	v_cndmask_b32_e64 v38, v38, v24, s[98:99]
	v_cmp_eq_u32_e64 s[98:99], 10, v10
	v_cndmask_b32_e64 v38, v38, v25, s[100:101]
	v_cmp_eq_u32_e64 s[100:101], 11, v10
	v_cndmask_b32_e32 v38, v38, v26, vcc
	v_cmp_eq_u32_e32 vcc, 12, v10
	v_cndmask_b32_e64 v38, v38, v27, s[98:99]
	v_cmp_eq_u32_e64 s[98:99], 13, v10
	v_cndmask_b32_e64 v38, v38, v28, s[100:101]
	v_cmp_eq_u32_e64 s[100:101], 14, v10
	v_cndmask_b32_e32 v38, v38, v29, vcc
	v_cmp_eq_u32_e32 vcc, 15, v10
	v_cndmask_b32_e64 v38, v38, v30, s[98:99]
	v_cndmask_b32_e64 v38, v38, v31, s[100:101]
	v_cndmask_b32_e32 v10, v38, v3, vcc
	v_cmp_gt_u32_e32 vcc, 16, v37
	v_cmp_eq_u32_e64 s[98:99], 1, v36
	v_cmp_eq_u32_e64 s[100:101], 2, v36
	v_cndmask_b32_e32 v37, 0, v85, vcc
	v_and_b32_e32 v10, 0x7f, v10
	v_cmp_eq_u32_e32 vcc, 3, v36
	v_cndmask_b32_e64 v37, v37, v86, s[98:99]
	v_cmp_eq_u32_e64 s[98:99], 4, v36
	v_cndmask_b32_e64 v37, v37, v87, s[100:101]
	v_cmp_eq_u32_e64 s[100:101], 5, v36
	v_cndmask_b32_e32 v37, v37, v88, vcc
	v_cmp_eq_u32_e32 vcc, 6, v36
	v_cndmask_b32_e64 v37, v37, v89, s[98:99]
	v_cmp_eq_u32_e64 s[98:99], 7, v36
	v_cndmask_b32_e64 v37, v37, v90, s[100:101]
	v_cmp_eq_u32_e64 s[100:101], 8, v36
	v_cndmask_b32_e32 v37, v37, v91, vcc
	v_cmp_eq_u32_e32 vcc, 9, v36
	v_cndmask_b32_e64 v37, v37, v92, s[98:99]
	v_cmp_eq_u32_e64 s[98:99], 10, v36
	v_cndmask_b32_e64 v37, v37, v93, s[100:101]
	v_cmp_eq_u32_e64 s[100:101], 11, v36
	v_cndmask_b32_e32 v37, v37, v94, vcc
	v_cmp_eq_u32_e32 vcc, 12, v36
	v_cndmask_b32_e64 v37, v37, v95, s[98:99]
	v_cmp_eq_u32_e64 s[98:99], 13, v36
	v_cndmask_b32_e64 v37, v37, v96, s[100:101]
	v_cmp_eq_u32_e64 s[100:101], 14, v36
	v_cndmask_b32_e32 v37, v37, v97, vcc
	v_cmp_eq_u32_e32 vcc, 15, v36
	v_cndmask_b32_e64 v37, v37, v98, s[98:99]
	v_cndmask_b32_e64 v37, v37, v99, s[100:101]
	v_cndmask_b32_e32 v36, v37, v100, vcc
	v_lshlrev_b32_e32 v36, 7, v36
	v_and_b32_e32 v36, 0x3f80, v36
	v_bitop3_b32 v10, v10, s82, v36 bitop3:0x36
	v_not_b32_e32 v36, v9
	v_bitop3_b32 v37, v9, s78, v9 bitop3:0xc
	v_bitop3_b32 v9, v9, 15, v9 bitop3:0xc
	v_cmp_eq_u32_e32 vcc, 0, v9
	v_cmp_eq_u32_e64 s[98:99], 1, v9
	v_cmp_eq_u32_e64 s[100:101], 2, v9
	v_cndmask_b32_e32 v38, 0, v12, vcc
	v_bfe_u32 v36, v36, 4, 4
	v_cmp_eq_u32_e32 vcc, 3, v9
	v_cndmask_b32_e64 v38, v38, v18, s[98:99]
	v_cmp_eq_u32_e64 s[98:99], 4, v9
	v_cndmask_b32_e64 v38, v38, v19, s[100:101]
	v_cmp_eq_u32_e64 s[100:101], 5, v9
	v_cndmask_b32_e32 v38, v38, v20, vcc
	v_cmp_eq_u32_e32 vcc, 6, v9
	v_cndmask_b32_e64 v38, v38, v21, s[98:99]
	v_cmp_eq_u32_e64 s[98:99], 7, v9
	v_cndmask_b32_e64 v38, v38, v22, s[100:101]
	v_cmp_eq_u32_e64 s[100:101], 8, v9
	v_cndmask_b32_e32 v38, v38, v23, vcc
	v_cmp_eq_u32_e32 vcc, 9, v9
	v_cndmask_b32_e64 v38, v38, v24, s[98:99]
	v_cmp_eq_u32_e64 s[98:99], 10, v9
	v_cndmask_b32_e64 v38, v38, v25, s[100:101]
	v_cmp_eq_u32_e64 s[100:101], 11, v9
	v_cndmask_b32_e32 v38, v38, v26, vcc
	v_cmp_eq_u32_e32 vcc, 12, v9
	v_cndmask_b32_e64 v38, v38, v27, s[98:99]
	v_cmp_eq_u32_e64 s[98:99], 13, v9
	v_cndmask_b32_e64 v38, v38, v28, s[100:101]
	v_cmp_eq_u32_e64 s[100:101], 14, v9
	v_cndmask_b32_e32 v38, v38, v29, vcc
	v_cmp_eq_u32_e32 vcc, 15, v9
	v_cndmask_b32_e64 v38, v38, v30, s[98:99]
	v_cndmask_b32_e64 v38, v38, v31, s[100:101]
	v_cndmask_b32_e32 v9, v38, v3, vcc
	v_cmp_gt_u32_e32 vcc, 16, v37
	v_cmp_eq_u32_e64 s[98:99], 1, v36
	v_cmp_eq_u32_e64 s[100:101], 2, v36
	v_cndmask_b32_e32 v37, 0, v85, vcc
	v_and_b32_e32 v9, 0x7f, v9
	v_cmp_eq_u32_e32 vcc, 3, v36
	v_cndmask_b32_e64 v37, v37, v86, s[98:99]
	v_cmp_eq_u32_e64 s[98:99], 4, v36
	v_cndmask_b32_e64 v37, v37, v87, s[100:101]
	v_cmp_eq_u32_e64 s[100:101], 5, v36
	v_cndmask_b32_e32 v37, v37, v88, vcc
	v_cmp_eq_u32_e32 vcc, 6, v36
	v_cndmask_b32_e64 v37, v37, v89, s[98:99]
	v_cmp_eq_u32_e64 s[98:99], 7, v36
	v_cndmask_b32_e64 v37, v37, v90, s[100:101]
	v_cmp_eq_u32_e64 s[100:101], 8, v36
	v_cndmask_b32_e32 v37, v37, v91, vcc
	v_cmp_eq_u32_e32 vcc, 9, v36
	v_cndmask_b32_e64 v37, v37, v92, s[98:99]
	v_cmp_eq_u32_e64 s[98:99], 10, v36
	v_cndmask_b32_e64 v37, v37, v93, s[100:101]
	v_cmp_eq_u32_e64 s[100:101], 11, v36
	v_cndmask_b32_e32 v37, v37, v94, vcc
	v_cmp_eq_u32_e32 vcc, 12, v36
	v_cndmask_b32_e64 v37, v37, v95, s[98:99]
	v_cmp_eq_u32_e64 s[98:99], 13, v36
	v_cndmask_b32_e64 v37, v37, v96, s[100:101]
	v_cmp_eq_u32_e64 s[100:101], 14, v36
	v_cndmask_b32_e32 v37, v37, v97, vcc
	v_cmp_eq_u32_e32 vcc, 15, v36
	v_cndmask_b32_e64 v37, v37, v98, s[98:99]
	v_cndmask_b32_e64 v37, v37, v99, s[100:101]
	v_cndmask_b32_e32 v36, v37, v100, vcc
	v_lshlrev_b32_e32 v36, 7, v36
	v_and_b32_e32 v36, 0x3f80, v36
	v_bitop3_b32 v9, v9, s82, v36 bitop3:0x36
	v_not_b32_e32 v36, v8
	v_bitop3_b32 v37, v8, s78, v8 bitop3:0xc
	v_bitop3_b32 v8, v8, 15, v8 bitop3:0xc
	v_cmp_eq_u32_e32 vcc, 0, v8
	v_cmp_eq_u32_e64 s[98:99], 1, v8
	v_cmp_eq_u32_e64 s[100:101], 2, v8
	v_cndmask_b32_e32 v38, 0, v12, vcc
	v_bfe_u32 v36, v36, 4, 4
	v_cmp_eq_u32_e32 vcc, 3, v8
	v_cndmask_b32_e64 v38, v38, v18, s[98:99]
	v_cmp_eq_u32_e64 s[98:99], 4, v8
	v_cndmask_b32_e64 v38, v38, v19, s[100:101]
	v_cmp_eq_u32_e64 s[100:101], 5, v8
	v_cndmask_b32_e32 v38, v38, v20, vcc
	v_cmp_eq_u32_e32 vcc, 6, v8
	v_cndmask_b32_e64 v38, v38, v21, s[98:99]
	v_cmp_eq_u32_e64 s[98:99], 7, v8
	v_cndmask_b32_e64 v38, v38, v22, s[100:101]
	v_cmp_eq_u32_e64 s[100:101], 8, v8
	v_cndmask_b32_e32 v38, v38, v23, vcc
	v_cmp_eq_u32_e32 vcc, 9, v8
	v_cndmask_b32_e64 v38, v38, v24, s[98:99]
	v_cmp_eq_u32_e64 s[98:99], 10, v8
	v_cndmask_b32_e64 v38, v38, v25, s[100:101]
	v_cmp_eq_u32_e64 s[100:101], 11, v8
	v_cndmask_b32_e32 v38, v38, v26, vcc
	v_cmp_eq_u32_e32 vcc, 12, v8
	v_cndmask_b32_e64 v38, v38, v27, s[98:99]
	v_cmp_eq_u32_e64 s[98:99], 13, v8
	v_cndmask_b32_e64 v38, v38, v28, s[100:101]
	v_cmp_eq_u32_e64 s[100:101], 14, v8
	v_cndmask_b32_e32 v38, v38, v29, vcc
	v_cmp_eq_u32_e32 vcc, 15, v8
	v_cndmask_b32_e64 v38, v38, v30, s[98:99]
	v_cndmask_b32_e64 v38, v38, v31, s[100:101]
	v_cndmask_b32_e32 v8, v38, v3, vcc
	v_cmp_gt_u32_e32 vcc, 16, v37
	v_cmp_eq_u32_e64 s[98:99], 1, v36
	v_cmp_eq_u32_e64 s[100:101], 2, v36
	v_cndmask_b32_e32 v37, 0, v85, vcc
	v_and_b32_e32 v8, 0x7f, v8
	v_cmp_eq_u32_e32 vcc, 3, v36
	v_cndmask_b32_e64 v37, v37, v86, s[98:99]
	v_cmp_eq_u32_e64 s[98:99], 4, v36
	v_cndmask_b32_e64 v37, v37, v87, s[100:101]
	v_cmp_eq_u32_e64 s[100:101], 5, v36
	v_cndmask_b32_e32 v37, v37, v88, vcc
	v_cmp_eq_u32_e32 vcc, 6, v36
	v_cndmask_b32_e64 v37, v37, v89, s[98:99]
	v_cmp_eq_u32_e64 s[98:99], 7, v36
	v_cndmask_b32_e64 v37, v37, v90, s[100:101]
	v_cmp_eq_u32_e64 s[100:101], 8, v36
	v_cndmask_b32_e32 v37, v37, v91, vcc
	v_cmp_eq_u32_e32 vcc, 9, v36
	v_cndmask_b32_e64 v37, v37, v92, s[98:99]
	v_cmp_eq_u32_e64 s[98:99], 10, v36
	v_cndmask_b32_e64 v37, v37, v93, s[100:101]
	v_cmp_eq_u32_e64 s[100:101], 11, v36
	v_cndmask_b32_e32 v37, v37, v94, vcc
	v_cmp_eq_u32_e32 vcc, 12, v36
	v_cndmask_b32_e64 v37, v37, v95, s[98:99]
	v_cmp_eq_u32_e64 s[98:99], 13, v36
	v_cndmask_b32_e64 v37, v37, v96, s[100:101]
	v_cmp_eq_u32_e64 s[100:101], 14, v36
	v_cndmask_b32_e32 v37, v37, v97, vcc
	v_cmp_eq_u32_e32 vcc, 15, v36
	v_cndmask_b32_e64 v37, v37, v98, s[98:99]
	v_cndmask_b32_e64 v37, v37, v99, s[100:101]
	v_cndmask_b32_e32 v36, v37, v100, vcc
	v_lshlrev_b32_e32 v36, 7, v36
	v_and_b32_e32 v36, 0x3f80, v36
	v_bitop3_b32 v8, v8, s82, v36 bitop3:0x36
	v_not_b32_e32 v36, v15
	v_bitop3_b32 v37, v15, s78, v15 bitop3:0xc
	v_bitop3_b32 v15, v15, 15, v15 bitop3:0xc
	v_cmp_eq_u32_e32 vcc, 0, v15
	v_cmp_eq_u32_e64 s[98:99], 1, v15
	v_cmp_eq_u32_e64 s[100:101], 2, v15
	v_cndmask_b32_e32 v38, 0, v12, vcc
	v_bfe_u32 v36, v36, 4, 4
	v_cmp_eq_u32_e32 vcc, 3, v15
	v_cndmask_b32_e64 v38, v38, v18, s[98:99]
	v_cmp_eq_u32_e64 s[98:99], 4, v15
	v_cndmask_b32_e64 v38, v38, v19, s[100:101]
	v_cmp_eq_u32_e64 s[100:101], 5, v15
	v_cndmask_b32_e32 v38, v38, v20, vcc
	v_cmp_eq_u32_e32 vcc, 6, v15
	v_cndmask_b32_e64 v38, v38, v21, s[98:99]
	v_cmp_eq_u32_e64 s[98:99], 7, v15
	v_cndmask_b32_e64 v38, v38, v22, s[100:101]
	v_cmp_eq_u32_e64 s[100:101], 8, v15
	v_cndmask_b32_e32 v38, v38, v23, vcc
	v_cmp_eq_u32_e32 vcc, 9, v15
	v_cndmask_b32_e64 v38, v38, v24, s[98:99]
	v_cmp_eq_u32_e64 s[98:99], 10, v15
	v_cndmask_b32_e64 v38, v38, v25, s[100:101]
	v_cmp_eq_u32_e64 s[100:101], 11, v15
	v_cndmask_b32_e32 v38, v38, v26, vcc
	v_cmp_eq_u32_e32 vcc, 12, v15
	v_cndmask_b32_e64 v38, v38, v27, s[98:99]
	v_cmp_eq_u32_e64 s[98:99], 13, v15
	v_cndmask_b32_e64 v38, v38, v28, s[100:101]
	v_cmp_eq_u32_e64 s[100:101], 14, v15
	v_cndmask_b32_e32 v38, v38, v29, vcc
	v_cmp_eq_u32_e32 vcc, 15, v15
	v_cndmask_b32_e64 v38, v38, v30, s[98:99]
	v_cndmask_b32_e64 v38, v38, v31, s[100:101]
	v_cndmask_b32_e32 v15, v38, v3, vcc
	v_cmp_gt_u32_e32 vcc, 16, v37
	v_cmp_eq_u32_e64 s[98:99], 1, v36
	v_cmp_eq_u32_e64 s[100:101], 2, v36
	v_cndmask_b32_e32 v37, 0, v85, vcc
	v_and_b32_e32 v15, 0x7f, v15
	v_cmp_eq_u32_e32 vcc, 3, v36
	v_cndmask_b32_e64 v37, v37, v86, s[98:99]
	v_cmp_eq_u32_e64 s[98:99], 4, v36
	v_cndmask_b32_e64 v37, v37, v87, s[100:101]
	v_cmp_eq_u32_e64 s[100:101], 5, v36
	v_cndmask_b32_e32 v37, v37, v88, vcc
	v_cmp_eq_u32_e32 vcc, 6, v36
	v_cndmask_b32_e64 v37, v37, v89, s[98:99]
	v_cmp_eq_u32_e64 s[98:99], 7, v36
	v_cndmask_b32_e64 v37, v37, v90, s[100:101]
	v_cmp_eq_u32_e64 s[100:101], 8, v36
	v_cndmask_b32_e32 v37, v37, v91, vcc
	v_cmp_eq_u32_e32 vcc, 9, v36
	v_cndmask_b32_e64 v37, v37, v92, s[98:99]
	v_cmp_eq_u32_e64 s[98:99], 10, v36
	v_cndmask_b32_e64 v37, v37, v93, s[100:101]
	v_cmp_eq_u32_e64 s[100:101], 11, v36
	v_cndmask_b32_e32 v37, v37, v94, vcc
	v_cmp_eq_u32_e32 vcc, 12, v36
	v_cndmask_b32_e64 v37, v37, v95, s[98:99]
	v_cmp_eq_u32_e64 s[98:99], 13, v36
	v_cndmask_b32_e64 v37, v37, v96, s[100:101]
	v_cmp_eq_u32_e64 s[100:101], 14, v36
	v_cndmask_b32_e32 v37, v37, v97, vcc
	v_cmp_eq_u32_e32 vcc, 15, v36
	v_cndmask_b32_e64 v37, v37, v98, s[98:99]
	v_cndmask_b32_e64 v37, v37, v99, s[100:101]
	v_cndmask_b32_e32 v36, v37, v100, vcc
	v_lshlrev_b32_e32 v36, 7, v36
	v_and_b32_e32 v36, 0x3f80, v36
	v_bitop3_b32 v15, v15, s82, v36 bitop3:0x36
	v_not_b32_e32 v36, v14
	v_bitop3_b32 v37, v14, s78, v14 bitop3:0xc
	v_bitop3_b32 v14, v14, 15, v14 bitop3:0xc
	v_cmp_eq_u32_e32 vcc, 0, v14
	v_cmp_eq_u32_e64 s[98:99], 1, v14
	v_cmp_eq_u32_e64 s[100:101], 2, v14
	v_cndmask_b32_e32 v38, 0, v12, vcc
	v_bfe_u32 v36, v36, 4, 4
	v_cmp_eq_u32_e32 vcc, 3, v14
	v_cndmask_b32_e64 v38, v38, v18, s[98:99]
	v_cmp_eq_u32_e64 s[98:99], 4, v14
	v_cndmask_b32_e64 v38, v38, v19, s[100:101]
	v_cmp_eq_u32_e64 s[100:101], 5, v14
	v_cndmask_b32_e32 v38, v38, v20, vcc
	v_cmp_eq_u32_e32 vcc, 6, v14
	v_cndmask_b32_e64 v38, v38, v21, s[98:99]
	v_cmp_eq_u32_e64 s[98:99], 7, v14
	v_cndmask_b32_e64 v38, v38, v22, s[100:101]
	v_cmp_eq_u32_e64 s[100:101], 8, v14
	v_cndmask_b32_e32 v38, v38, v23, vcc
	v_cmp_eq_u32_e32 vcc, 9, v14
	v_cndmask_b32_e64 v38, v38, v24, s[98:99]
	v_cmp_eq_u32_e64 s[98:99], 10, v14
	v_cndmask_b32_e64 v38, v38, v25, s[100:101]
	v_cmp_eq_u32_e64 s[100:101], 11, v14
	v_cndmask_b32_e32 v38, v38, v26, vcc
	v_cmp_eq_u32_e32 vcc, 12, v14
	v_cndmask_b32_e64 v38, v38, v27, s[98:99]
	v_cmp_eq_u32_e64 s[98:99], 13, v14
	v_cndmask_b32_e64 v38, v38, v28, s[100:101]
	v_cmp_eq_u32_e64 s[100:101], 14, v14
	v_cndmask_b32_e32 v38, v38, v29, vcc
	v_cmp_eq_u32_e32 vcc, 15, v14
	v_cndmask_b32_e64 v38, v38, v30, s[98:99]
	v_cndmask_b32_e64 v38, v38, v31, s[100:101]
	v_cndmask_b32_e32 v14, v38, v3, vcc
	v_cmp_gt_u32_e32 vcc, 16, v37
	v_cmp_eq_u32_e64 s[98:99], 1, v36
	v_cmp_eq_u32_e64 s[100:101], 2, v36
	v_cndmask_b32_e32 v37, 0, v85, vcc
	v_and_b32_e32 v14, 0x7f, v14
	v_cmp_eq_u32_e32 vcc, 3, v36
	v_cndmask_b32_e64 v37, v37, v86, s[98:99]
	v_cmp_eq_u32_e64 s[98:99], 4, v36
	v_cndmask_b32_e64 v37, v37, v87, s[100:101]
	v_cmp_eq_u32_e64 s[100:101], 5, v36
	v_cndmask_b32_e32 v37, v37, v88, vcc
	v_cmp_eq_u32_e32 vcc, 6, v36
	v_cndmask_b32_e64 v37, v37, v89, s[98:99]
	v_cmp_eq_u32_e64 s[98:99], 7, v36
	v_cndmask_b32_e64 v37, v37, v90, s[100:101]
	v_cmp_eq_u32_e64 s[100:101], 8, v36
	v_cndmask_b32_e32 v37, v37, v91, vcc
	v_cmp_eq_u32_e32 vcc, 9, v36
	v_cndmask_b32_e64 v37, v37, v92, s[98:99]
	v_cmp_eq_u32_e64 s[98:99], 10, v36
	v_cndmask_b32_e64 v37, v37, v93, s[100:101]
	v_cmp_eq_u32_e64 s[100:101], 11, v36
	v_cndmask_b32_e32 v37, v37, v94, vcc
	v_cmp_eq_u32_e32 vcc, 12, v36
	v_cndmask_b32_e64 v37, v37, v95, s[98:99]
	v_cmp_eq_u32_e64 s[98:99], 13, v36
	v_cndmask_b32_e64 v37, v37, v96, s[100:101]
	v_cmp_eq_u32_e64 s[100:101], 14, v36
	v_cndmask_b32_e32 v37, v37, v97, vcc
	v_cmp_eq_u32_e32 vcc, 15, v36
	v_cndmask_b32_e64 v37, v37, v98, s[98:99]
	v_cndmask_b32_e64 v37, v37, v99, s[100:101]
	v_cndmask_b32_e32 v36, v37, v100, vcc
	v_lshlrev_b32_e32 v36, 7, v36
	v_and_b32_e32 v36, 0x3f80, v36
	v_bitop3_b32 v14, v14, s82, v36 bitop3:0x36
	v_not_b32_e32 v36, v13
	v_bitop3_b32 v37, v13, s78, v13 bitop3:0xc
	v_bitop3_b32 v13, v13, 15, v13 bitop3:0xc
	v_cmp_eq_u32_e32 vcc, 0, v13
	v_cmp_eq_u32_e64 s[98:99], 1, v13
	v_cmp_eq_u32_e64 s[100:101], 2, v13
	v_cndmask_b32_e32 v38, 0, v12, vcc
	v_bfe_u32 v36, v36, 4, 4
	v_cmp_eq_u32_e32 vcc, 3, v13
	v_cndmask_b32_e64 v38, v38, v18, s[98:99]
	v_cmp_eq_u32_e64 s[98:99], 4, v13
	v_cndmask_b32_e64 v38, v38, v19, s[100:101]
	v_cmp_eq_u32_e64 s[100:101], 5, v13
	v_cndmask_b32_e32 v38, v38, v20, vcc
	v_cmp_eq_u32_e32 vcc, 6, v13
	v_cndmask_b32_e64 v38, v38, v21, s[98:99]
	v_cmp_eq_u32_e64 s[98:99], 7, v13
	v_cndmask_b32_e64 v38, v38, v22, s[100:101]
	v_cmp_eq_u32_e64 s[100:101], 8, v13
	v_cndmask_b32_e32 v38, v38, v23, vcc
	v_cmp_eq_u32_e32 vcc, 9, v13
	v_cndmask_b32_e64 v38, v38, v24, s[98:99]
	v_cmp_eq_u32_e64 s[98:99], 10, v13
	v_cndmask_b32_e64 v38, v38, v25, s[100:101]
	v_cmp_eq_u32_e64 s[100:101], 11, v13
	v_cndmask_b32_e32 v38, v38, v26, vcc
	v_cmp_eq_u32_e32 vcc, 12, v13
	v_cndmask_b32_e64 v38, v38, v27, s[98:99]
	v_cmp_eq_u32_e64 s[98:99], 13, v13
	v_cndmask_b32_e64 v38, v38, v28, s[100:101]
	v_cmp_eq_u32_e64 s[100:101], 14, v13
	v_cndmask_b32_e32 v38, v38, v29, vcc
	v_cmp_eq_u32_e32 vcc, 15, v13
	v_cndmask_b32_e64 v38, v38, v30, s[98:99]
	v_cndmask_b32_e64 v38, v38, v31, s[100:101]
	v_cndmask_b32_e32 v13, v38, v3, vcc
	v_cmp_gt_u32_e32 vcc, 16, v37
	v_cmp_eq_u32_e64 s[98:99], 1, v36
	v_cmp_eq_u32_e64 s[100:101], 2, v36
	v_cndmask_b32_e32 v37, 0, v85, vcc
	v_and_b32_e32 v13, 0x7f, v13
	v_cmp_eq_u32_e32 vcc, 3, v36
	v_cndmask_b32_e64 v37, v37, v86, s[98:99]
	v_cmp_eq_u32_e64 s[98:99], 4, v36
	v_cndmask_b32_e64 v37, v37, v87, s[100:101]
	v_cmp_eq_u32_e64 s[100:101], 5, v36
	v_cndmask_b32_e32 v37, v37, v88, vcc
	v_cmp_eq_u32_e32 vcc, 6, v36
	v_cndmask_b32_e64 v37, v37, v89, s[98:99]
	v_cmp_eq_u32_e64 s[98:99], 7, v36
	v_cndmask_b32_e64 v37, v37, v90, s[100:101]
	v_cmp_eq_u32_e64 s[100:101], 8, v36
	v_cndmask_b32_e32 v37, v37, v91, vcc
	v_cmp_eq_u32_e32 vcc, 9, v36
	v_cndmask_b32_e64 v37, v37, v92, s[98:99]
	v_cmp_eq_u32_e64 s[98:99], 10, v36
	v_cndmask_b32_e64 v37, v37, v93, s[100:101]
	v_cmp_eq_u32_e64 s[100:101], 11, v36
	v_cndmask_b32_e32 v37, v37, v94, vcc
	v_cmp_eq_u32_e32 vcc, 12, v36
	v_cndmask_b32_e64 v37, v37, v95, s[98:99]
	v_cmp_eq_u32_e64 s[98:99], 13, v36
	v_cndmask_b32_e64 v37, v37, v96, s[100:101]
	v_cmp_eq_u32_e64 s[100:101], 14, v36
	v_cndmask_b32_e32 v37, v37, v97, vcc
	v_cmp_eq_u32_e32 vcc, 15, v36
	v_cndmask_b32_e64 v37, v37, v98, s[98:99]
	v_cndmask_b32_e64 v37, v37, v99, s[100:101]
	v_cndmask_b32_e32 v36, v37, v100, vcc
	v_lshlrev_b32_e32 v36, 7, v36
	v_and_b32_e32 v36, 0x3f80, v36
	v_bitop3_b32 v13, v13, s82, v36 bitop3:0x36
	v_not_b32_e32 v36, v32
	v_bitop3_b32 v37, v32, s78, v32 bitop3:0xc
	v_bitop3_b32 v32, v32, 15, v32 bitop3:0xc
	v_cmp_eq_u32_e32 vcc, 0, v32
	v_cmp_eq_u32_e64 s[98:99], 1, v32
	v_cmp_eq_u32_e64 s[100:101], 2, v32
	v_cndmask_b32_e32 v12, 0, v12, vcc
	v_cmp_eq_u32_e32 vcc, 3, v32
	v_cndmask_b32_e64 v12, v12, v18, s[98:99]
	v_cmp_eq_u32_e64 s[98:99], 4, v32
	v_cndmask_b32_e64 v12, v12, v19, s[100:101]
	v_bfe_u32 v18, v36, 4, 4
	v_cmp_eq_u32_e64 s[100:101], 5, v32
	v_cndmask_b32_e32 v12, v12, v20, vcc
	v_cmp_eq_u32_e32 vcc, 6, v32
	v_cndmask_b32_e64 v12, v12, v21, s[98:99]
	v_cmp_eq_u32_e64 s[98:99], 7, v32
	v_cndmask_b32_e64 v12, v12, v22, s[100:101]
	v_cmp_eq_u32_e64 s[100:101], 8, v32
	v_cndmask_b32_e32 v12, v12, v23, vcc
	v_cmp_eq_u32_e32 vcc, 9, v32
	v_cndmask_b32_e64 v12, v12, v24, s[98:99]
	v_cmp_eq_u32_e64 s[98:99], 10, v32
	v_cndmask_b32_e64 v12, v12, v25, s[100:101]
	v_cmp_eq_u32_e64 s[100:101], 11, v32
	v_cndmask_b32_e32 v12, v12, v26, vcc
	v_cmp_eq_u32_e32 vcc, 12, v32
	v_cndmask_b32_e64 v12, v12, v27, s[98:99]
	v_cmp_eq_u32_e64 s[98:99], 13, v32
	v_cndmask_b32_e64 v12, v12, v28, s[100:101]
	v_cmp_eq_u32_e64 s[100:101], 14, v32
	v_cndmask_b32_e32 v12, v12, v29, vcc
	v_cmp_eq_u32_e32 vcc, 15, v32
	v_cndmask_b32_e64 v12, v12, v30, s[98:99]
	v_cndmask_b32_e64 v12, v12, v31, s[100:101]
	v_cndmask_b32_e32 v12, v12, v3, vcc
	v_cmp_gt_u32_e32 vcc, 16, v37
	v_cmp_eq_u32_e64 s[98:99], 1, v18
	v_cmp_eq_u32_e64 s[100:101], 2, v18
	v_cndmask_b32_e32 v19, 0, v85, vcc
	v_and_b32_e32 v12, 0x7f, v12
	v_cmp_eq_u32_e32 vcc, 3, v18
	v_cndmask_b32_e64 v19, v19, v86, s[98:99]
	v_cmp_eq_u32_e64 s[98:99], 4, v18
	v_cndmask_b32_e64 v19, v19, v87, s[100:101]
	v_cmp_eq_u32_e64 s[100:101], 5, v18
	v_cndmask_b32_e32 v19, v19, v88, vcc
	v_cmp_eq_u32_e32 vcc, 6, v18
	v_cndmask_b32_e64 v19, v19, v89, s[98:99]
	v_cmp_eq_u32_e64 s[98:99], 7, v18
	v_cndmask_b32_e64 v19, v19, v90, s[100:101]
	v_cmp_eq_u32_e64 s[100:101], 8, v18
	v_cndmask_b32_e32 v19, v19, v91, vcc
	v_cmp_eq_u32_e32 vcc, 9, v18
	v_cndmask_b32_e64 v19, v19, v92, s[98:99]
	v_cmp_eq_u32_e64 s[98:99], 10, v18
	v_cndmask_b32_e64 v19, v19, v93, s[100:101]
	v_cmp_eq_u32_e64 s[100:101], 11, v18
	v_cndmask_b32_e32 v19, v19, v94, vcc
	v_cmp_eq_u32_e32 vcc, 12, v18
	v_cndmask_b32_e64 v19, v19, v95, s[98:99]
	v_cmp_eq_u32_e64 s[98:99], 13, v18
	v_cndmask_b32_e64 v19, v19, v96, s[100:101]
	v_cmp_eq_u32_e64 s[100:101], 14, v18
	v_cndmask_b32_e32 v19, v19, v97, vcc
	v_cmp_eq_u32_e32 vcc, 15, v18
	v_cndmask_b32_e64 v19, v19, v98, s[98:99]
	v_cndmask_b32_e64 v19, v19, v99, s[100:101]
	v_cndmask_b32_e32 v18, v19, v100, vcc
	v_lshlrev_b32_e32 v18, 7, v18
	v_and_b32_e32 v18, 0x3f80, v18
	v_cmp_eq_u32_e32 vcc, 15, v34
	v_bitop3_b32 v12, v12, s82, v18 bitop3:0x36
	v_lshlrev_b32_e32 v18, 7, v33
	v_cndmask_b32_e32 v3, v35, v3, vcc
	v_and_b32_e32 v3, 0x7f, v3
	v_and_b32_e32 v18, 0x3f80, v18
	v_bitop3_b32 v3, v3, s82, v18 bitop3:0x36
	v_lshl_add_u64 v[18:19], v[16:17], 0, s[42:43]
	v_add_co_u32_e32 v16, vcc, 0x34000000, v16
	s_nop 1
	v_addc_co_u32_e32 v17, vcc, 0, v17, vcc
	global_store_dwordx4 v[16:17], v[12:15], off
	global_store_dwordx4 v[18:19], v[8:11], off offset:16
	global_store_dwordx4 v[18:19], v[4:7], off offset:32
	global_store_dwordx4 v[18:19], v[0:3], off offset:48
	s_branch .LBB0_1055
